# attention online softmax: keep the running row max unless some row's tile max exceeds it by more than 8 (log2 units), so the O/l rescale is skipped on most K tiles (exact same softmax, f32 stats)
# speedup vs baseline: 1.0033x; 1.0033x over previous
.Lattn_nopf:
	v_lshl_add_u64 v[130:131], s[86:87], 0, v[170:171]
	v_add_co_u32_e32 v132, vcc, s88, v130
	s_nop 1
	v_addc_co_u32_e32 v133, vcc, 0, v131, vcc
	v_add_co_u32_e32 v130, vcc, s17, v130
	global_load_dwordx4 v[158:161], v[132:133], off offset:512
	global_load_dwordx4 v[154:157], v[132:133], off offset:1024
	global_load_dwordx4 v[150:153], v[132:133], off offset:2560
	global_load_dwordx4 v[146:149], v[132:133], off offset:3072
	v_addc_co_u32_e32 v131, vcc, 0, v131, vcc
	v_lshl_add_u64 v[132:133], s[86:87], 0, v[168:169]
	v_add_co_u32_e32 v132, vcc, 0xae6f000, v132
	s_nop 1
	v_addc_co_u32_e32 v133, vcc, 0, v133, vcc
	global_load_dwordx4 v[138:141], v[130:131], off offset:512
	global_load_dwordx4 v[134:137], v[130:131], off offset:2560
	global_load_dwordx4 v[142:145], v[132:133], off offset:512
	s_nop 0
	global_load_dwordx4 v[130:133], v[132:133], off offset:2560
	v_mov_b32_e32 v188, s8
	ds_read_b32 v190, v188 offset:1024
	s_cmp_lt_u32 s9, 6
	s_cbranch_scc0 .Lattn_far_p
	s_waitcnt vmcnt(8)
	v_subrev_u32_e32 v177, 64, v177
	v_max3_f32 v231, v98, v99, v100
	v_max3_f32 v231, v231, v101, v102
	v_max3_f32 v231, v231, v103, v104
	v_max3_f32 v231, v231, v105, v106
	v_max3_f32 v231, v231, v107, v108
	v_max3_f32 v231, v231, v109, v110
	v_max3_f32 v231, v231, v111, v112
	v_max3_f32 v231, v231, v113, v114
	v_max3_f32 v231, v231, v115, v116
	v_max3_f32 v231, v231, v117, v118
	v_max3_f32 v231, v231, v119, v120
	v_max3_f32 v231, v231, v121, v122
	v_max3_f32 v231, v231, v123, v124
	v_max3_f32 v231, v231, v125, v126
	v_max3_f32 v231, v231, v127, v128
	v_max_f32_e32 v231, v231, v129
	s_waitcnt lgkmcnt(0)
	v_fma_f32 v231, v231, v216, v190
	ds_bpermute_b32 v233, v249, v231
	v_max3_f32 v234, v66, v67, v68
	v_max3_f32 v234, v234, v69, v70
	v_max3_f32 v234, v234, v71, v72
	v_max3_f32 v234, v234, v73, v74
	v_max3_f32 v234, v234, v75, v76
	v_max3_f32 v234, v234, v77, v78
	v_max3_f32 v234, v234, v79, v80
	v_max3_f32 v234, v234, v81, v82
	v_max3_f32 v234, v234, v83, v84
	v_max3_f32 v234, v234, v85, v86
	v_max3_f32 v234, v234, v87, v88
	v_max3_f32 v234, v234, v89, v90
	v_max3_f32 v234, v234, v91, v92
	v_max3_f32 v234, v234, v93, v94
	v_max3_f32 v234, v234, v95, v96
	v_max_f32_e32 v234, v234, v97
	v_fma_f32 v234, v234, v216, v190
	ds_bpermute_b32 v235, v249, v234
	s_waitcnt lgkmcnt(1)
	v_max3_f32 v236, v199, v231, v233
	v_sub_f32_e32 v226, v199, v236
	v_cmp_gt_f32_e32 vcc, 0xc1000000, v226
	s_cbranch_vccnz .Lattn_near_p_ka
	v_mov_b32_e32 v236, v199
.Lattn_near_p_ka:
	v_sub_f32_e32 v226, v199, v236
	v_sub_f32_e32 v238, v190, v236
	v_sub_f32_e32 v239, v190, v236
	v_exp_f32_e32 v226, v226
	v_pk_fma_f32 v[98:99], v[98:99], v[216:217], v[238:239]
	v_pk_fma_f32 v[100:101], v[100:101], v[216:217], v[238:239]
	v_pk_fma_f32 v[102:103], v[102:103], v[216:217], v[238:239]
	v_pk_fma_f32 v[104:105], v[104:105], v[216:217], v[238:239]
	v_pk_fma_f32 v[106:107], v[106:107], v[216:217], v[238:239]
	v_pk_fma_f32 v[108:109], v[108:109], v[216:217], v[238:239]
	v_pk_fma_f32 v[110:111], v[110:111], v[216:217], v[238:239]
	v_pk_fma_f32 v[112:113], v[112:113], v[216:217], v[238:239]
	v_pk_fma_f32 v[114:115], v[114:115], v[216:217], v[238:239]
	v_pk_fma_f32 v[116:117], v[116:117], v[216:217], v[238:239]
	v_pk_fma_f32 v[118:119], v[118:119], v[216:217], v[238:239]
	v_pk_fma_f32 v[120:121], v[120:121], v[216:217], v[238:239]
	v_pk_fma_f32 v[122:123], v[122:123], v[216:217], v[238:239]
	v_pk_fma_f32 v[124:125], v[124:125], v[216:217], v[238:239]
	v_pk_fma_f32 v[126:127], v[126:127], v[216:217], v[238:239]
	v_pk_fma_f32 v[128:129], v[128:129], v[216:217], v[238:239]
	v_exp_f32_e32 v98, v98
	v_exp_f32_e32 v99, v99
	v_exp_f32_e32 v100, v100
	v_exp_f32_e32 v101, v101
	v_exp_f32_e32 v102, v102
	v_exp_f32_e32 v103, v103
	v_exp_f32_e32 v104, v104
	v_exp_f32_e32 v105, v105
	v_exp_f32_e32 v106, v106
	v_exp_f32_e32 v107, v107
	v_exp_f32_e32 v108, v108
	v_exp_f32_e32 v109, v109
	v_exp_f32_e32 v110, v110
	v_exp_f32_e32 v111, v111
	v_exp_f32_e32 v112, v112
	v_exp_f32_e32 v113, v113
	v_exp_f32_e32 v114, v114
	v_exp_f32_e32 v115, v115
	v_exp_f32_e32 v116, v116
	v_exp_f32_e32 v117, v117
	v_exp_f32_e32 v118, v118
	v_exp_f32_e32 v119, v119
	v_exp_f32_e32 v120, v120
	v_exp_f32_e32 v121, v121
	v_exp_f32_e32 v122, v122
	v_exp_f32_e32 v123, v123
	v_exp_f32_e32 v124, v124
	v_exp_f32_e32 v125, v125
	v_exp_f32_e32 v126, v126
	v_exp_f32_e32 v127, v127
	v_exp_f32_e32 v128, v128
	v_exp_f32_e32 v129, v129
	s_waitcnt lgkmcnt(0)
	v_max3_f32 v218, v189, v234, v235
	v_sub_f32_e32 v228, v189, v218
	v_cmp_gt_f32_e32 vcc, 0xc1000000, v228
	s_cbranch_vccnz .Lattn_near_p_kb
	v_mov_b32_e32 v218, v189
.Lattn_near_p_kb:
	v_sub_f32_e32 v228, v189, v218
	v_sub_f32_e32 v202, v190, v218
	v_sub_f32_e32 v203, v190, v218
	v_exp_f32_e32 v228, v228
	v_pk_fma_f32 v[66:67], v[66:67], v[216:217], v[202:203]
	v_pk_fma_f32 v[68:69], v[68:69], v[216:217], v[202:203]
	v_pk_fma_f32 v[70:71], v[70:71], v[216:217], v[202:203]
	v_pk_fma_f32 v[72:73], v[72:73], v[216:217], v[202:203]
	v_pk_fma_f32 v[74:75], v[74:75], v[216:217], v[202:203]
	v_pk_fma_f32 v[76:77], v[76:77], v[216:217], v[202:203]
	v_pk_fma_f32 v[78:79], v[78:79], v[216:217], v[202:203]
	v_pk_fma_f32 v[80:81], v[80:81], v[216:217], v[202:203]
	v_pk_fma_f32 v[82:83], v[82:83], v[216:217], v[202:203]
	v_pk_fma_f32 v[84:85], v[84:85], v[216:217], v[202:203]
	v_pk_fma_f32 v[86:87], v[86:87], v[216:217], v[202:203]
	v_pk_fma_f32 v[88:89], v[88:89], v[216:217], v[202:203]
	v_pk_fma_f32 v[90:91], v[90:91], v[216:217], v[202:203]
	v_pk_fma_f32 v[92:93], v[92:93], v[216:217], v[202:203]
	v_pk_fma_f32 v[94:95], v[94:95], v[216:217], v[202:203]
	v_pk_fma_f32 v[96:97], v[96:97], v[216:217], v[202:203]
	v_exp_f32_e32 v66, v66
	v_exp_f32_e32 v67, v67
	v_exp_f32_e32 v68, v68
	v_exp_f32_e32 v69, v69
	v_exp_f32_e32 v70, v70
	v_exp_f32_e32 v71, v71
	v_exp_f32_e32 v72, v72
	v_exp_f32_e32 v73, v73
	v_exp_f32_e32 v74, v74
	v_exp_f32_e32 v75, v75
	v_exp_f32_e32 v76, v76
	v_exp_f32_e32 v77, v77
	v_exp_f32_e32 v78, v78
	v_exp_f32_e32 v79, v79
	v_exp_f32_e32 v80, v80
	v_exp_f32_e32 v81, v81
	v_exp_f32_e32 v82, v82
	v_exp_f32_e32 v83, v83
	v_exp_f32_e32 v84, v84
	v_exp_f32_e32 v85, v85
	v_exp_f32_e32 v86, v86
	v_exp_f32_e32 v87, v87
	v_exp_f32_e32 v88, v88
	v_exp_f32_e32 v89, v89
	v_exp_f32_e32 v90, v90
	v_exp_f32_e32 v91, v91
	v_exp_f32_e32 v92, v92
	v_exp_f32_e32 v93, v93
	v_exp_f32_e32 v94, v94
	v_exp_f32_e32 v95, v95
	v_exp_f32_e32 v96, v96
	v_exp_f32_e32 v97, v97
	v_pk_add_f32 v[212:213], v[98:99], v[100:101]
	v_pk_add_f32 v[214:215], v[102:103], v[104:105]
	v_pk_add_f32 v[212:213], v[212:213], v[106:107]
	v_pk_add_f32 v[214:215], v[214:215], v[108:109]
	v_pk_add_f32 v[212:213], v[212:213], v[110:111]
	v_pk_add_f32 v[214:215], v[214:215], v[112:113]
	v_pk_add_f32 v[212:213], v[212:213], v[114:115]
	v_pk_add_f32 v[214:215], v[214:215], v[116:117]
	v_pk_add_f32 v[212:213], v[212:213], v[118:119]
	v_pk_add_f32 v[214:215], v[214:215], v[120:121]
	v_pk_add_f32 v[212:213], v[212:213], v[122:123]
	v_pk_add_f32 v[214:215], v[214:215], v[124:125]
	v_pk_add_f32 v[212:213], v[212:213], v[126:127]
	v_pk_add_f32 v[214:215], v[214:215], v[128:129]
	v_pk_add_f32 v[212:213], v[212:213], v[214:215]
	v_add_f32_e32 v210, v212, v213
	ds_bpermute_b32 v211, v249, v210
	v_pk_add_f32 v[220:221], v[66:67], v[68:69]
	v_pk_add_f32 v[222:223], v[70:71], v[72:73]
	v_pk_add_f32 v[220:221], v[220:221], v[74:75]
	v_pk_add_f32 v[222:223], v[222:223], v[76:77]
	v_pk_add_f32 v[220:221], v[220:221], v[78:79]
	v_pk_add_f32 v[222:223], v[222:223], v[80:81]
	v_pk_add_f32 v[220:221], v[220:221], v[82:83]
	v_pk_add_f32 v[222:223], v[222:223], v[84:85]
	v_pk_add_f32 v[220:221], v[220:221], v[86:87]
	v_pk_add_f32 v[222:223], v[222:223], v[88:89]
	v_pk_add_f32 v[220:221], v[220:221], v[90:91]
	v_pk_add_f32 v[222:223], v[222:223], v[92:93]
	v_pk_add_f32 v[220:221], v[220:221], v[94:95]
	v_pk_add_f32 v[222:223], v[222:223], v[96:97]
	v_pk_add_f32 v[220:221], v[220:221], v[222:223]
	v_add_f32_e32 v224, v220, v221
	ds_bpermute_b32 v225, v249, v224
	v_cmp_neq_f32_e32 vcc, 1.0, v226
	s_cbranch_vccz .Lattn_near_p_sa
	v_mov_b32_e32 v227, v226
	v_pk_mul_f32 v[64:65], v[64:65], v[226:227]
	v_pk_mul_f32 v[62:63], v[62:63], v[226:227]
	v_pk_mul_f32 v[60:61], v[60:61], v[226:227]
	v_pk_mul_f32 v[58:59], v[58:59], v[226:227]
	v_pk_mul_f32 v[56:57], v[56:57], v[226:227]
	v_pk_mul_f32 v[54:55], v[54:55], v[226:227]
	v_pk_mul_f32 v[52:53], v[52:53], v[226:227]
	v_pk_mul_f32 v[50:51], v[50:51], v[226:227]
	v_pk_mul_f32 v[48:49], v[48:49], v[226:227]
	v_pk_mul_f32 v[46:47], v[46:47], v[226:227]
	v_pk_mul_f32 v[44:45], v[44:45], v[226:227]
	v_pk_mul_f32 v[42:43], v[42:43], v[226:227]
	v_pk_mul_f32 v[40:41], v[40:41], v[226:227]
	v_pk_mul_f32 v[38:39], v[38:39], v[226:227]
	v_pk_mul_f32 v[36:37], v[36:37], v[226:227]
	v_pk_mul_f32 v[34:35], v[34:35], v[226:227]

.Lattn_far_p:
	s_waitcnt vmcnt(8)
	v_lshl_add_u32 v191, v177, 2, s8
	v_subrev_u32_e32 v177, 64, v177
	s_add_i32 s2, s8, 0x200
	v_add_u32_e32 v192, 0xfffffff4, v191
	v_min_i32_e32 v192, s2, v192
	ds_read2_b32 v[200:201], v192 offset0:131 offset1:130
	ds_read2_b32 v[202:203], v192 offset0:129 offset1:128
	v_add_u32_e32 v193, 0xffffffd4, v191
	v_min_i32_e32 v193, s2, v193
	ds_read2_b32 v[204:205], v193 offset0:131 offset1:130
	ds_read2_b32 v[206:207], v193 offset0:129 offset1:128
	v_add_u32_e32 v192, 0xffffffb4, v191
	v_min_i32_e32 v192, s2, v192
	ds_read2_b32 v[208:209], v192 offset0:131 offset1:130
	ds_read2_b32 v[210:211], v192 offset0:129 offset1:128
	v_add_u32_e32 v193, 0xffffff94, v191
	v_min_i32_e32 v193, s2, v193
	ds_read2_b32 v[212:213], v193 offset0:131 offset1:130
	ds_read2_b32 v[214:215], v193 offset0:129 offset1:128
	v_add_u32_e32 v192, 0xffffff74, v191
	v_min_i32_e32 v192, s2, v192
	ds_read2_b32 v[218:219], v192 offset0:131 offset1:130
	ds_read2_b32 v[220:221], v192 offset0:129 offset1:128
	v_add_u32_e32 v193, 0xffffff54, v191
	v_min_i32_e32 v193, s2, v193
	ds_read2_b32 v[222:223], v193 offset0:131 offset1:130
	ds_read2_b32 v[224:225], v193 offset0:129 offset1:128
	v_add_u32_e32 v192, 0xffffff34, v191
	v_min_i32_e32 v192, s2, v192
	ds_read2_b32 v[226:227], v192 offset0:131 offset1:130
	ds_read2_b32 v[228:229], v192 offset0:129 offset1:128
	s_waitcnt lgkmcnt(6)
	v_pk_fma_f32 v[66:67], v[66:67], v[216:217], v[200:201]
	v_pk_fma_f32 v[68:69], v[68:69], v[216:217], v[202:203]
	v_pk_fma_f32 v[70:71], v[70:71], v[216:217], v[204:205]
	v_pk_fma_f32 v[72:73], v[72:73], v[216:217], v[206:207]
	v_pk_fma_f32 v[74:75], v[74:75], v[216:217], v[208:209]
	v_pk_fma_f32 v[76:77], v[76:77], v[216:217], v[210:211]
	v_pk_fma_f32 v[78:79], v[78:79], v[216:217], v[212:213]
	v_pk_fma_f32 v[80:81], v[80:81], v[216:217], v[214:215]
	v_add_u32_e32 v193, 0xffffff14, v191
	v_min_i32_e32 v193, s2, v193
	ds_read2_b32 v[230:231], v193 offset0:131 offset1:130
	ds_read2_b32 v[232:233], v193 offset0:129 offset1:128
	v_add_u32_e32 v192, 0xfffffef4, v191
	v_min_i32_e32 v192, s2, v192
	ds_read2_b32 v[200:201], v192 offset0:131 offset1:130
	ds_read2_b32 v[202:203], v192 offset0:129 offset1:128
	v_add_u32_e32 v193, 0xfffffed4, v191
	v_min_i32_e32 v193, s2, v193
	ds_read2_b32 v[204:205], v193 offset0:131 offset1:130
	ds_read2_b32 v[206:207], v193 offset0:129 offset1:128
	v_add_u32_e32 v192, 0xfffffeb4, v191
	v_min_i32_e32 v192, s2, v192
	ds_read2_b32 v[208:209], v192 offset0:131 offset1:130
	ds_read2_b32 v[210:211], v192 offset0:129 offset1:128
	s_waitcnt lgkmcnt(6)
	v_pk_fma_f32 v[98:99], v[98:99], v[216:217], v[218:219]
	v_pk_fma_f32 v[100:101], v[100:101], v[216:217], v[220:221]
	v_pk_fma_f32 v[102:103], v[102:103], v[216:217], v[222:223]
	v_pk_fma_f32 v[104:105], v[104:105], v[216:217], v[224:225]
	v_pk_fma_f32 v[106:107], v[106:107], v[216:217], v[226:227]
	v_pk_fma_f32 v[108:109], v[108:109], v[216:217], v[228:229]
	v_pk_fma_f32 v[110:111], v[110:111], v[216:217], v[230:231]
	v_pk_fma_f32 v[112:113], v[112:113], v[216:217], v[232:233]
	v_pk_fma_f32 v[82:83], v[82:83], v[216:217], v[218:219]
	v_pk_fma_f32 v[84:85], v[84:85], v[216:217], v[220:221]
	v_pk_fma_f32 v[86:87], v[86:87], v[216:217], v[222:223]
	v_pk_fma_f32 v[88:89], v[88:89], v[216:217], v[224:225]
	v_pk_fma_f32 v[90:91], v[90:91], v[216:217], v[226:227]
	v_pk_fma_f32 v[92:93], v[92:93], v[216:217], v[228:229]
	v_pk_fma_f32 v[94:95], v[94:95], v[216:217], v[230:231]
	v_pk_fma_f32 v[96:97], v[96:97], v[216:217], v[232:233]
	v_add_u32_e32 v193, 0xfffffe94, v191
	v_min_i32_e32 v193, s2, v193
	ds_read2_b32 v[212:213], v193 offset0:131 offset1:130
	ds_read2_b32 v[214:215], v193 offset0:129 offset1:128
	s_waitcnt lgkmcnt(0)
	v_pk_fma_f32 v[114:115], v[114:115], v[216:217], v[200:201]
	v_pk_fma_f32 v[116:117], v[116:117], v[216:217], v[202:203]
	v_pk_fma_f32 v[118:119], v[118:119], v[216:217], v[204:205]
	v_pk_fma_f32 v[120:121], v[120:121], v[216:217], v[206:207]
	v_pk_fma_f32 v[122:123], v[122:123], v[216:217], v[208:209]
	v_pk_fma_f32 v[124:125], v[124:125], v[216:217], v[210:211]
	v_pk_fma_f32 v[126:127], v[126:127], v[216:217], v[212:213]
	v_pk_fma_f32 v[128:129], v[128:129], v[216:217], v[214:215]
	v_max3_f32 v231, v98, v99, v100
	v_max3_f32 v231, v231, v101, v102
	v_max3_f32 v231, v231, v103, v104
	v_max3_f32 v231, v231, v105, v106
	v_max3_f32 v231, v231, v107, v108
	v_max3_f32 v231, v231, v109, v110
	v_max3_f32 v231, v231, v111, v112
	v_max3_f32 v231, v231, v113, v114
	v_max3_f32 v231, v231, v115, v116
	v_max3_f32 v231, v231, v117, v118
	v_max3_f32 v231, v231, v119, v120
	v_max3_f32 v231, v231, v121, v122
	v_max3_f32 v231, v231, v123, v124
	v_max3_f32 v231, v231, v125, v126
	v_max3_f32 v231, v231, v127, v128
	v_max_f32_e32 v231, v231, v129
	ds_bpermute_b32 v233, v249, v231
	v_max3_f32 v234, v66, v67, v68
	v_max3_f32 v234, v234, v69, v70
	v_max3_f32 v234, v234, v71, v72
	v_max3_f32 v234, v234, v73, v74
	v_max3_f32 v234, v234, v75, v76
	v_max3_f32 v234, v234, v77, v78
	v_max3_f32 v234, v234, v79, v80
	v_max3_f32 v234, v234, v81, v82
	v_max3_f32 v234, v234, v83, v84
	v_max3_f32 v234, v234, v85, v86
	v_max3_f32 v234, v234, v87, v88
	v_max3_f32 v234, v234, v89, v90
	v_max3_f32 v234, v234, v91, v92
	v_max3_f32 v234, v234, v93, v94
	v_max3_f32 v234, v234, v95, v96
	v_max_f32_e32 v234, v234, v97
	ds_bpermute_b32 v235, v249, v234
	s_waitcnt lgkmcnt(1)
	v_max3_f32 v236, v199, v231, v233
	v_sub_f32_e32 v226, v199, v236
	v_cmp_gt_f32_e32 vcc, 0xc1000000, v226
	s_cbranch_vccnz .Lattn_far_p_ka
	v_mov_b32_e32 v236, v199
.Lattn_far_p_ka:
	v_sub_f32_e32 v226, v199, v236
	v_sub_f32_e32 v238, 0, v236
	v_sub_f32_e32 v239, 0, v236
	v_exp_f32_e32 v226, v226
	v_pk_add_f32 v[98:99], v[98:99], v[238:239]
	v_pk_add_f32 v[100:101], v[100:101], v[238:239]
	v_pk_add_f32 v[102:103], v[102:103], v[238:239]
	v_pk_add_f32 v[104:105], v[104:105], v[238:239]
	v_pk_add_f32 v[106:107], v[106:107], v[238:239]
	v_pk_add_f32 v[108:109], v[108:109], v[238:239]
	v_pk_add_f32 v[110:111], v[110:111], v[238:239]
	v_pk_add_f32 v[112:113], v[112:113], v[238:239]
	v_pk_add_f32 v[114:115], v[114:115], v[238:239]
	v_pk_add_f32 v[116:117], v[116:117], v[238:239]
	v_pk_add_f32 v[118:119], v[118:119], v[238:239]
	v_pk_add_f32 v[120:121], v[120:121], v[238:239]
	v_pk_add_f32 v[122:123], v[122:123], v[238:239]
	v_pk_add_f32 v[124:125], v[124:125], v[238:239]
	v_pk_add_f32 v[126:127], v[126:127], v[238:239]
	v_pk_add_f32 v[128:129], v[128:129], v[238:239]
	v_exp_f32_e32 v98, v98
	v_exp_f32_e32 v99, v99
	v_exp_f32_e32 v100, v100
	v_exp_f32_e32 v101, v101
	v_exp_f32_e32 v102, v102
	v_exp_f32_e32 v103, v103
	v_exp_f32_e32 v104, v104
	v_exp_f32_e32 v105, v105
	v_exp_f32_e32 v106, v106
	v_exp_f32_e32 v107, v107
	v_exp_f32_e32 v108, v108
	v_exp_f32_e32 v109, v109
	v_exp_f32_e32 v110, v110
	v_exp_f32_e32 v111, v111
	v_exp_f32_e32 v112, v112
	v_exp_f32_e32 v113, v113
	v_exp_f32_e32 v114, v114
	v_exp_f32_e32 v115, v115
	v_exp_f32_e32 v116, v116
	v_exp_f32_e32 v117, v117
	v_exp_f32_e32 v118, v118
	v_exp_f32_e32 v119, v119
	v_exp_f32_e32 v120, v120
	v_exp_f32_e32 v121, v121
	v_exp_f32_e32 v122, v122
	v_exp_f32_e32 v123, v123
	v_exp_f32_e32 v124, v124
	v_exp_f32_e32 v125, v125
	v_exp_f32_e32 v126, v126
	v_exp_f32_e32 v127, v127
	v_exp_f32_e32 v128, v128
	v_exp_f32_e32 v129, v129
	s_waitcnt lgkmcnt(0)
	v_max3_f32 v218, v189, v234, v235
	v_sub_f32_e32 v228, v189, v218
	v_cmp_gt_f32_e32 vcc, 0xc1000000, v228
	s_cbranch_vccnz .Lattn_far_p_kb
	v_mov_b32_e32 v218, v189
.Lattn_far_p_kb:
	v_sub_f32_e32 v228, v189, v218
	v_sub_f32_e32 v202, 0, v218
	v_sub_f32_e32 v203, 0, v218
	v_exp_f32_e32 v228, v228
	v_pk_add_f32 v[66:67], v[66:67], v[202:203]
	v_pk_add_f32 v[68:69], v[68:69], v[202:203]
	v_pk_add_f32 v[70:71], v[70:71], v[202:203]
	v_pk_add_f32 v[72:73], v[72:73], v[202:203]
	v_pk_add_f32 v[74:75], v[74:75], v[202:203]
	v_pk_add_f32 v[76:77], v[76:77], v[202:203]
	v_pk_add_f32 v[78:79], v[78:79], v[202:203]
	v_pk_add_f32 v[80:81], v[80:81], v[202:203]
	v_pk_add_f32 v[82:83], v[82:83], v[202:203]
	v_pk_add_f32 v[84:85], v[84:85], v[202:203]
	v_pk_add_f32 v[86:87], v[86:87], v[202:203]
	v_pk_add_f32 v[88:89], v[88:89], v[202:203]
	v_pk_add_f32 v[90:91], v[90:91], v[202:203]
	v_pk_add_f32 v[92:93], v[92:93], v[202:203]
	v_pk_add_f32 v[94:95], v[94:95], v[202:203]
	v_pk_add_f32 v[96:97], v[96:97], v[202:203]
	v_exp_f32_e32 v66, v66
	v_exp_f32_e32 v67, v67
	v_exp_f32_e32 v68, v68
	v_exp_f32_e32 v69, v69
	v_exp_f32_e32 v70, v70
	v_exp_f32_e32 v71, v71
	v_exp_f32_e32 v72, v72
	v_exp_f32_e32 v73, v73
	v_exp_f32_e32 v74, v74
	v_exp_f32_e32 v75, v75
	v_exp_f32_e32 v76, v76
	v_exp_f32_e32 v77, v77
	v_exp_f32_e32 v78, v78
	v_exp_f32_e32 v79, v79
	v_exp_f32_e32 v80, v80
	v_exp_f32_e32 v81, v81
	v_exp_f32_e32 v82, v82
	v_exp_f32_e32 v83, v83
	v_exp_f32_e32 v84, v84
	v_exp_f32_e32 v85, v85
	v_exp_f32_e32 v86, v86
	v_exp_f32_e32 v87, v87
	v_exp_f32_e32 v88, v88
	v_exp_f32_e32 v89, v89
	v_exp_f32_e32 v90, v90
	v_exp_f32_e32 v91, v91
	v_exp_f32_e32 v92, v92
	v_exp_f32_e32 v93, v93
	v_exp_f32_e32 v94, v94
	v_exp_f32_e32 v95, v95
	v_exp_f32_e32 v96, v96
	v_exp_f32_e32 v97, v97
	v_pk_add_f32 v[212:213], v[98:99], v[100:101]
	v_pk_add_f32 v[214:215], v[102:103], v[104:105]
	v_pk_add_f32 v[212:213], v[212:213], v[106:107]
	v_pk_add_f32 v[214:215], v[214:215], v[108:109]
	v_pk_add_f32 v[212:213], v[212:213], v[110:111]
	v_pk_add_f32 v[214:215], v[214:215], v[112:113]
	v_pk_add_f32 v[212:213], v[212:213], v[114:115]
	v_pk_add_f32 v[214:215], v[214:215], v[116:117]
	v_pk_add_f32 v[212:213], v[212:213], v[118:119]
	v_pk_add_f32 v[214:215], v[214:215], v[120:121]
	v_pk_add_f32 v[212:213], v[212:213], v[122:123]
	v_pk_add_f32 v[214:215], v[214:215], v[124:125]
	v_pk_add_f32 v[212:213], v[212:213], v[126:127]
	v_pk_add_f32 v[214:215], v[214:215], v[128:129]
	v_pk_add_f32 v[212:213], v[212:213], v[214:215]
	v_add_f32_e32 v210, v212, v213
	ds_bpermute_b32 v211, v249, v210
	v_pk_add_f32 v[220:221], v[66:67], v[68:69]
	v_pk_add_f32 v[222:223], v[70:71], v[72:73]
	v_pk_add_f32 v[220:221], v[220:221], v[74:75]
	v_pk_add_f32 v[222:223], v[222:223], v[76:77]
	v_pk_add_f32 v[220:221], v[220:221], v[78:79]
	v_pk_add_f32 v[222:223], v[222:223], v[80:81]
	v_pk_add_f32 v[220:221], v[220:221], v[82:83]
	v_pk_add_f32 v[222:223], v[222:223], v[84:85]
	v_pk_add_f32 v[220:221], v[220:221], v[86:87]
	v_pk_add_f32 v[222:223], v[222:223], v[88:89]
	v_pk_add_f32 v[220:221], v[220:221], v[90:91]
	v_pk_add_f32 v[222:223], v[222:223], v[92:93]
	v_pk_add_f32 v[220:221], v[220:221], v[94:95]
	v_pk_add_f32 v[222:223], v[222:223], v[96:97]
	v_pk_add_f32 v[220:221], v[220:221], v[222:223]
	v_add_f32_e32 v224, v220, v221
	ds_bpermute_b32 v225, v249, v224
	v_cmp_neq_f32_e32 vcc, 1.0, v226
	s_cbranch_vccz .Lattn_far_p_sa
	v_mov_b32_e32 v227, v226
	v_pk_mul_f32 v[64:65], v[64:65], v[226:227]
	v_pk_mul_f32 v[62:63], v[62:63], v[226:227]
	v_pk_mul_f32 v[60:61], v[60:61], v[226:227]
	v_pk_mul_f32 v[58:59], v[58:59], v[226:227]
	v_pk_mul_f32 v[56:57], v[56:57], v[226:227]
	v_pk_mul_f32 v[54:55], v[54:55], v[226:227]
	v_pk_mul_f32 v[52:53], v[52:53], v[226:227]
	v_pk_mul_f32 v[50:51], v[50:51], v[226:227]
	v_pk_mul_f32 v[48:49], v[48:49], v[226:227]
	v_pk_mul_f32 v[46:47], v[46:47], v[226:227]
	v_pk_mul_f32 v[44:45], v[44:45], v[226:227]
	v_pk_mul_f32 v[42:43], v[42:43], v[226:227]
	v_pk_mul_f32 v[40:41], v[40:41], v[226:227]
	v_pk_mul_f32 v[38:39], v[38:39], v[226:227]
	v_pk_mul_f32 v[36:37], v[36:37], v[226:227]
	v_pk_mul_f32 v[34:35], v[34:35], v[226:227]
